# top-k rank loop in the compressed-attention unit rotated: next ds_read2 pair issued before the compares of the current pair
# baseline (speedup 1.0000x reference)
.LBB0_759:
	v_lshl_add_u32 v7, s35, 9, v78
	s_mov_b64 s[28:29], s[4:5]
	s_and_saveexec_b64 s[54:55], s[38:39]
	s_cbranch_execz .LBB0_766
	v_lshl_add_u32 v4, v7, 2, 0
	v_add_u32_e32 v4, 0x12000, v4
	ds_read_b32 v4, v4
	v_lshlrev_b32_e32 v5, 2, v6
	v_and_b32_e32 v8, 0xffffff80, v5
	s_mov_b32 s12, 2
	v_add_u32_e32 v10, s85, v8
	s_waitcnt lgkmcnt(0)
	v_mov_b32_e32 v5, v4
	v_mov_b32_e32 v9, 0
	s_mov_b32 s28, 1
	s_mov_b32 s29, s34
	v_mov_b32_e32 v11, 0
	ds_read2_b32 v[12:13], v10 offset1:1
	v_add_u32_e32 v10, 8, v10
.LBB0_761:
	v_cmp_lt_u32_e32 vcc, s28, v0
	v_cmp_lt_u32_e64 s[42:43], s12, v3
	s_add_i32 s28, s28, 2
	s_add_i32 s12, s12, 2
	s_waitcnt lgkmcnt(0)
	v_mov_b32_e32 v14, v12
	v_mov_b32_e32 v15, v13
	ds_read2_b32 v[12:13], v10 offset1:1
	v_cmp_eq_f32_e64 s[48:49], v14, v4
	v_cmp_eq_f32_e64 s[50:51], v15, v5
	v_cmp_gt_f32_e64 s[44:45], v15, v5
	v_cmp_gt_f32_e64 s[46:47], v14, v4
	s_and_b64 s[42:43], s[50:51], s[42:43]
	s_and_b64 s[48:49], s[48:49], vcc
	s_add_i32 s29, s29, -2
	s_or_b64 vcc, s[46:47], s[48:49]
	s_or_b64 s[42:43], s[44:45], s[42:43]
	v_add_u32_e32 v10, 8, v10
	v_addc_co_u32_e64 v11, s[42:43], 0, v11, s[42:43]
	s_cmp_lg_u32 s29, 0
	v_addc_co_u32_e32 v9, vcc, 0, v9, vcc
	s_cbranch_scc1 .LBB0_761
	s_waitcnt lgkmcnt(0)
	s_andn2_b64 vcc, exec, s[52:53]
	v_add_u32_e32 v5, v9, v11
	s_cbranch_vccnz .LBB0_765
	v_add_u32_e32 v8, s26, v8
	s_mov_b32 s12, s23
